# blocked up/down projection: p8 rounds 0-3, p9 first half, p8 rounds 4-7, p9 second half (HB half stays in last-level cache)
# baseline (speedup 1.0000x reference)
; __global__ void __launch_bounds__(512, 2) fwd_kernel(Params p) {
;     ...
;     for (int ph = p.ph_lo; ph < p.ph_hi; ++ph) {
;         if (ph > p.ph_lo) { if (p.ph_hi < 0) grid.sync(); else xcd_barrier(xbar); }
;     ...
;         case 8: { pg8::Gemm g{TB, Wt_up, M, FF, D, nullptr, nullptr}; pg8::StaticOrder S; S.init(M, FF, G, bid); EpiB<1> E{HB, FF, 1.f, nullptr, Fold{ST1, CSB + CS_UP, FF}}; pg8::gemm_phase<EpiB<1>>(lds, g, S, E, tid); } break;
;         case 9: { pg8::Gemm g{HB, Wt_dn, M, D, FF, nullptr, nullptr}; pg8::StaticOrder S; S.init(M, D, G, bid, 1);
;             EpiRes E{nullptr, nullptr, TB, p.in[z0 + 17] + (size_t)l * D, p.in[z0 + 18] + (size_t)l * D, ST2, Fold{ST1, nullptr, 0}}; pg8::gemm_phase<EpiRes>(lds, g, S, E, tid); } break;
.LBB0_28:
	s_cmp_eq_u32 s84, 7
	s_cbranch_scc1 .Lblk_zero
	s_cmp_eq_u32 s84, 17
	s_cbranch_scc0 .Lblk_chk9
.Lblk_zero:
	s_mov_b32 s101, 0
.Lblk_chk9:
	s_cmp_eq_u32 s84, 9
	s_cbranch_scc1 .Lblk_is9
	s_cmp_eq_u32 s84, 19
	s_cbranch_scc0 .Lblk_inc
.Lblk_is9:
	s_cmp_eq_u32 s101, 0
	s_cbranch_scc0 .Lblk_second
	s_mov_b32 s101, 1
	s_add_i32 s84, s84, -2
	s_branch .Lblk_inc

;     __device__ bool next(int i, Unit& u) const {
;         const int nr = (nwg + G - 1) / G; if (i >= nr) return false;
;         const long L = (long)(rev ? nr - 1 - i : i) * G + c; if (L >= nwg) return false;
;         int wgid = (int)L; { const int q = nwg / NXCD, r = nwg % NXCD, xcd = wgid % NXCD, off = wgid / NXCD; wgid = (xcd < r ? xcd * (q + 1) : r * (q + 1) + (xcd - r) * q) + off; }
; __global__ void __launch_bounds__(512, 2) fwd_kernel(Params p) {
;     ...
;         const int l = ph / NPH, k = ph % NPH;
;         float* ST0 = (float*)(ws + WS_STATS) + (size_t)((3 * l + 0) & 1) * M * 64; float* ST1 = (float*)(ws + WS_STATS) + (size_t)((3 * l + 1) & 1) * M * 64;
;         float* ST2 = (float*)(ws + WS_STATS) + (size_t)((3 * l + 2) & 1) * M * 64;
;         const float* STP = ST1;
;         switch (k) {
.LBB0_96:
	s_andn2_b64 vcc, exec, s[0:1]
	s_cbranch_vccnz .LBB0_28
	s_mul_hi_i32 s0, s84, 0x66666667
	s_lshr_b32 s1, s0, 31
	s_ashr_i32 s0, s0, 2
	s_waitcnt lgkmcnt(0)
	s_add_i32 s4, s0, s1
	s_mul_i32 s0, s4, 10
	s_sub_i32 s85, s84, s0
	s_mov_b32 s2, s4
	s_add_u32 s0, s42, 0x1fd03600
	v_writelane_b32 v251, s2, 33
	s_addc_u32 s1, s43, 0
	s_nop 0
	v_writelane_b32 v251, s3, 34
	s_lshl_b32 s2, s4, 20
	s_and_b32 s2, s2, 0x100000
	s_lshl_b32 s4, s2, 2
	s_add_u32 s10, s0, s4
	s_addc_u32 s11, s1, 0
	s_xor_b32 s2, s2, 0x100000
	s_lshl_b32 s2, s2, 2
	s_add_u32 s0, s0, s2
	s_addc_u32 s1, s1, 0
	v_writelane_b32 v251, s0, 35
	s_nop 1
	v_writelane_b32 v251, s1, 36
	s_add_u32 s0, s42, 0x2e00000
	s_addc_u32 s1, s43, 0
	v_writelane_b32 v251, s0, 37
	s_nop 1
	v_writelane_b32 v251, s1, 38
	s_add_u32 s0, s42, 0x3400000
	s_addc_u32 s1, s43, 0
	v_writelane_b32 v251, s0, 39
	s_nop 1
	v_writelane_b32 v251, s1, 40
	s_add_u32 s0, s42, 0x5600000
	s_addc_u32 s1, s43, 0
	v_writelane_b32 v251, s0, 41
	s_nop 1
	v_writelane_b32 v251, s1, 42
	s_add_u32 s0, s42, 0xb600000
	s_addc_u32 s1, s43, 0
	v_writelane_b32 v251, s0, 43
	s_nop 1
	v_writelane_b32 v251, s1, 44
	s_add_u32 s0, s42, 0x1b600000
	s_addc_u32 s1, s43, 0
	v_writelane_b32 v251, s0, 45
	s_nop 1
	v_writelane_b32 v251, s1, 46
	s_add_u32 s0, s42, 0x1d600000
	s_addc_u32 s1, s43, 0
	v_writelane_b32 v251, s0, 47
	s_nop 1
	v_writelane_b32 v251, s1, 48
	s_add_u32 s0, s42, 0x1fa00000
	s_addc_u32 s1, s43, 0
	v_writelane_b32 v251, s0, 49
	s_cmp_lt_i32 s85, 5
	s_nop 0
	v_writelane_b32 v251, s1, 50
	v_writelane_b32 v251, s24, 51
	s_mov_b64 s[0:1], -1
	s_nop 0
	v_writelane_b32 v251, s25, 52
	v_writelane_b32 v251, s42, 53
	s_nop 1
	v_writelane_b32 v251, s43, 54
	s_cbranch_scc1 .LBB0_284
	s_add_u32 s8, s42, 0x3600000
	s_addc_u32 s9, s43, 0
	s_cmp_lt_i32 s85, 7
	s_cbranch_scc1 .LBB0_232
	s_cmp_lt_i32 s85, 8
	s_cbranch_scc1 .LBB0_183
	s_cmp_lt_i32 s85, 9
	s_cbranch_scc1 .LBB0_152
	s_cmp_eq_u32 s85, 9
	s_cbranch_scc0 .LBB0_151
	v_readlane_b32 s0, v251, 29
	v_readlane_b32 s1, v251, 30
	s_mov_b32 s4, s0
	s_ashr_i32 s5, s0, 31
	v_writelane_b32 v251, s0, 29
	v_readfirstlane_b32 s12, v210
	s_nop 0
	v_writelane_b32 v251, s1, 30
	s_lshl_b64 s[0:1], s[4:5], 3
	v_readlane_b32 s4, v250, 40
	s_add_u32 s0, s68, s0
	v_readlane_b32 s5, v250, 41
	s_addc_u32 s1, s69, s1
	s_andn2_b64 vcc, exec, s[4:5]
	s_cbranch_vccnz .LBB0_110
	v_readlane_b32 s5, v251, 28
	s_ashr_i32 s2, s5, 31
	v_readlane_b32 s4, v250, 43
	s_mul_i32 s4, s4, s101
	s_add_u32 s6, s4, s5
	v_readlane_b32 s4, v250, 42
	s_mul_i32 s4, s4, s101
	s_addc_u32 s7, s4, s2
	v_cmp_gt_i64_e32 vcc, s[6:7], v[170:171]
	s_mov_b64 s[4:5], 0
	s_cbranch_vccnz .LBB0_109
	s_ashr_i32 s2, s6, 31
	s_lshr_b32 s2, s2, 29
	s_add_i32 s2, s6, s2
	s_and_b32 s4, s2, -8
	s_sub_i32 s6, s6, s4
	s_cmp_gt_i32 s6, -1
	s_mov_b64 s[4:5], -1
	s_cbranch_scc0 .LBB0_106
	s_lshl_b32 s7, s6, 6
	s_mov_b64 s[4:5], 0

;     __device__ bool next(int i, Unit& u) const {
;         const int nr = (nwg + G - 1) / G; if (i >= nr) return false;
;         const long L = (long)(rev ? nr - 1 - i : i) * G + c; if (L >= nwg) return false;
;         int wgid = (int)L; { const int q = nwg / NXCD, r = nwg % NXCD, xcd = wgid % NXCD, off = wgid / NXCD; wgid = (xcd < r ? xcd * (q + 1) : r * (q + 1) + (xcd - r) * q) + off; }
; template <class Epi>
; __device__ __forceinline__ void gemm_phase(LAS unsigned char* lds, const Gemm g, const StaticOrder& S, const Epi& E, const int tid) {
;     ...
;         const bool has_next = S.next(ui + 1, nxt);
.LBB0_118:
	s_add_i32 s48, s25, 1
	s_cmp_ge_i32 s48, 1
	s_mov_b64 s[22:23], 0
	s_cbranch_scc1 .LBB0_125
	s_sub_i32 s15, s94, s25
	s_mul_hi_i32 s17, s15, s78
	s_mul_i32 s15, s15, s78
	v_readlane_b32 s18, v251, 28
	s_add_u32 s18, s15, s18
	s_addc_u32 s19, s17, s47
	v_cmp_gt_i64_e32 vcc, s[18:19], v[170:171]
	s_cbranch_vccnz .LBB0_125
	s_ashr_i32 s14, s18, 31
	s_lshr_b32 s14, s14, 29
	s_add_i32 s16, s18, s14
	s_and_b32 s14, s16, -8
	s_sub_i32 s17, s18, s14
	s_cmp_gt_i32 s17, -1
	s_mov_b64 s[14:15], -1
	s_cbranch_scc0 .LBB0_122
	s_lshl_b32 s18, s17, 6
	s_mov_b64 s[14:15], 0

; #define LAS __attribute__((address_space(3)))
; __device__ __forceinline__ float shflx(float v, int k, int lane) { return __int_as_float(__builtin_amdgcn_ds_bpermute((lane ^ k) << 2, __float_as_int(v))); }
;     __device__ __forceinline__ void prepare(const pg8::Unit& u, LAS unsigned char* lds, int par, int tid) const { F.prepare(u, lds, par, tid); }
;     __device__ __forceinline__ void prepare(const pg8::Unit& u, LAS unsigned char* lds, int par, int tid) const { F.prepare(u, lds, par, tid); }
;     __device__ __forceinline__ void prepare(const pg8::Unit& u, LAS unsigned char* lds, int par, int tid) const { F.prepare(u, lds, par, tid); }
;     __device__ bool next(int i, Unit& u) const {
;     ...
;         int wgid = (int)L; { const int q = nwg / NXCD, r = nwg % NXCD, xcd = wgid % NXCD, off = wgid / NXCD; wgid = (xcd < r ? xcd * (q + 1) : r * (q + 1) + (xcd - r) * q) + off; }
;         const int nig = WGM * nN, gid = wgid / nig, fm = gid * WGM, gsz = (nM - fm) < WGM ? (nM - fm) : WGM;
;         u.pm = fm + ((wgid % nig) % gsz); u.pn = (wgid % nig) / gsz; return true;
;     __device__ __forceinline__ void prepare(const pg8::Unit& u, LAS unsigned char* lds, int par, int tid) const {
;         if (stats == nullptr) return;
;         const int h = tid >> 8, tt = tid & 255, rl = tt >> 1, part = tt & 1, lrow = (rl >> 6) * 128 + h * 64 + (rl & 63);
;         const float* sp = stats + ((size_t)(u.pm * 256 + lrow) * 32 + part * 16) * 2;
;         float s1 = 0.f, s2 = 0.f;
; #pragma unroll
;         for (int i = 0; i < 8; ++i) { const f32x4 v = *(const f32x4*)(sp + 4 * i); s1 += v[0] + v[2]; s2 += v[1] + v[3]; }
;         s1 += shflx(s1, 1, tid & 63); s2 += shflx(s2, 1, tid & 63);
;         const float mu = s1 * (1.f / D), var = s2 * (1.f / D) - mu * mu, rstd = __builtin_amdgcn_rsqf(var + LN_EPS);
;         if (part == 0) { LAS float* rs = (LAS float*)(lds + RS_OFF) + (par * 256 + lrow) * 2; rs[0] = mu; rs[1] = rstd; }
.LBB0_158:
	s_ashr_i32 s0, s2, 3
	s_add_i32 s0, s5, s0
	s_lshl_b32 s1, s101, 7
	s_add_i32 s0, s0, s1
	s_lshl_b32 s100, s101, 2
	s_add_i32 s100, s100, 4
	s_ashr_i32 s1, s0, 31
	s_lshr_b32 s1, s1, 25
	s_add_i32 s1, s0, s1
	s_ashr_i32 s2, s1, 7
	s_and_b32 s1, s1, 0xff80
	s_sub_i32 s0, s0, s1
	s_bfe_i32 s1, s0, 0x80000
	s_bfe_u32 s1, s1, 0x2000d
	s_lshl_b32 s4, s2, 2
	s_add_i32 s2, s0, s1
	s_and_b32 s1, s2, 0xfc
	s_waitcnt vmcnt(0)
	v_ashrrev_i32_e32 v3, 2, v210
	s_sub_i32 s0, s0, s1
	v_and_b32_e32 v2, 0x80, v210
	v_and_b32_e32 v3, 0xffffffc0, v3
	s_sext_i32_i8 s0, s0
	v_lshrrev_b32_e32 v0, 1, v210
	v_add_u32_e32 v2, v3, v2
	s_add_i32 s24, s4, s0
	v_and_or_b32 v144, v0, 63, v2
	v_lshl_add_u32 v2, s24, 8, v144
	v_ashrrev_i32_e32 v3, 31, v2
	v_readlane_b32 s0, v251, 35
	v_and_b32_e32 v10, 1, v210
	v_lshlrev_b64 v[2:3], 8, v[2:3]
	v_readlane_b32 s1, v251, 36
	v_lshlrev_b32_e32 v0, 7, v10
	v_lshlrev_b32_e32 v11, 2, v210
	v_lshl_add_u64 v[2:3], s[0:1], 0, v[2:3]
	v_lshl_add_u64 v[6:7], v[2:3], 0, v[0:1]
	s_waitcnt lgkmcnt(0)
	global_load_dwordx4 v[2:5], v[6:7], off
	global_load_dwordx4 v[222:225], v[6:7], off offset:16
	global_load_dwordx4 v[226:229], v[6:7], off offset:32
	global_load_dwordx4 v[230:233], v[6:7], off offset:48
	global_load_dwordx4 v[234:237], v[6:7], off offset:64
	global_load_dwordx4 v[238:241], v[6:7], off offset:80
	global_load_dwordx4 v[242:245], v[6:7], off offset:96
	global_load_dwordx4 v[246:249], v[6:7], off offset:112
	v_bitop3_b32 v145, v11, 4, v205 bitop3:0x6c
	v_cmp_eq_u32_e64 s[0:1], 0, v10
	s_waitcnt vmcnt(0) lgkmcnt(0)
	v_add_f32_e32 v0, v2, v4
	v_add_f32_e32 v2, v3, v5
	v_add_f32_e32 v8, 0, v2
	v_add_f32_e32 v0, 0, v0
	v_add_f32_e32 v2, v222, v224
	v_add_f32_e32 v0, v0, v2
	v_add_f32_e32 v2, v223, v225
	v_add_f32_e32 v8, v8, v2
	v_add_f32_e32 v2, v226, v228
	v_add_f32_e32 v0, v0, v2
	v_add_f32_e32 v2, v227, v229
	v_add_f32_e32 v8, v8, v2
	v_add_f32_e32 v2, v230, v232
	v_add_f32_e32 v0, v0, v2
	v_add_f32_e32 v2, v231, v233
	v_add_f32_e32 v8, v8, v2
	v_add_f32_e32 v2, v234, v236
	v_add_f32_e32 v0, v0, v2
	v_add_f32_e32 v2, v235, v237
	v_add_f32_e32 v8, v8, v2
	v_add_f32_e32 v2, v238, v240
	v_add_f32_e32 v0, v0, v2
	v_add_f32_e32 v2, v239, v241
	v_add_f32_e32 v8, v8, v2
	v_add_f32_e32 v2, v242, v244
	v_add_f32_e32 v0, v0, v2
	v_add_f32_e32 v2, v243, v245
	v_add_f32_e32 v8, v8, v2
	v_add_f32_e32 v2, v246, v248
	v_add_f32_e32 v0, v0, v2
	v_add_f32_e32 v2, v247, v249
	v_add_f32_e32 v2, v8, v2
	ds_bpermute_b32 v3, v145, v0
	ds_bpermute_b32 v4, v145, v2
	s_and_saveexec_b64 s[4:5], s[0:1]
	s_cbranch_execz .LBB0_160
	s_waitcnt lgkmcnt(1)
	v_add_f32_e32 v0, v0, v3
	s_waitcnt lgkmcnt(0)
	v_add_f32_e32 v4, v2, v4
	v_mul_f32_e32 v2, 0x3a000000, v0
	v_mul_f32_e32 v0, v2, v2
	v_fma_f32 v0, v4, s61, -v0
	v_add_f32_e32 v0, 0x3727c5ac, v0
	v_rsq_f32_e32 v3, v0
	v_lshl_add_u32 v0, v144, 3, 0
	v_add_u32_e32 v0, 0x20000, v0
	ds_write_b64 v0, v[2:3]

; #define PG8_STAGE(bufoff, gbase, voff) do { _Pragma("unroll") for (int _i = 0; _i < 2; ++_i) \
;         __builtin_amdgcn_global_load_lds((const unsigned*)((const char*)(gbase) + (voff)[_i]), (LAS unsigned*)(lds + (bufoff) + ldsw + _i * 8192), 16, 0, 0); } while (0)
; #define PG8_WAIT_V(n) asm volatile("s_waitcnt vmcnt(" #n ")" ::: "memory")
; #define PG8_BAR __builtin_amdgcn_s_barrier()
; template <class Epi>
; __device__ __forceinline__ void gemm_phase(LAS unsigned char* lds, const Gemm g, const StaticOrder& S, const Epi& E, const int tid) {
;     const int wid = __builtin_amdgcn_readfirstlane(tid >> 6), lane = tid & 63, wr = wid >> 2, wc = wid & 3, fr = lane & 15, fq = lane >> 4;
;     const int K = g.K, nt = K / BK, ntt = Epi::TWO ? 2 * nt : nt;
;     unsigned voffA[2], voffB[2];
; #pragma unroll
;     for (int i = 0; i < 2; ++i) { int R, C; stage_rc(tid * 16 + i * 8192, R, C); const int Rb = (R >> 5) * 64 + ((R >> 2) & 3) * 16 + ((R >> 4) & 1) * 4 + (R & 3);
;         voffA[i] = (unsigned)(R * K + C) * 2u; voffB[i] = (unsigned)(Rb * K + C) * 2u; }
;     const size_t kstep = (size_t)(BK * 2);
;     const size_t hstep = (size_t)HALF * K * 2;
;     const size_t tstep = 2 * hstep;
;     const size_t bhs = (size_t)8 * K * 2;
;     const unsigned ldsw = (unsigned)wid * 1024u;
;     const int aoff = lds_byte(wr * 64 + fr, fq * 8), boff = lds_byte(wc * 32 + fr, fq * 8);
;     ...
;         PG8_STAGE(PG8_SB(1, 0), cB + kstep, voffB); PG8_STAGE(PG8_SA(1, 0), cA + kstep, voffA); PG8_STAGE(PG8_SB(1, 1), cB + bhs + kstep, voffB);
;         PG8_WAIT_V(6); PG8_BAR;
.LBB0_162:
	v_and_b32_e32 v18, 15, v210
	v_and_b32_e32 v19, 48, v210
	s_and_b32 s15, s13, 3
	v_lshl_or_b32 v148, s14, 6, v18
	s_lshl_b32 s13, s14, 13
	v_lshl_or_b32 v18, v18, 6, v19
	v_and_b32_e32 v11, 32, v11
	s_add_i32 m0, s2, 0x18000
	v_lshl_add_u64 v[6:7], v[6:7], 0, s[70:71]
	v_bitop3_b32 v20, v18, s13, v11 bitop3:0xde
	s_lshl_b32 s13, s15, 12
	s_waitcnt vmcnt(2)
	s_barrier
	global_load_lds_dwordx4 v[6:7], off
	v_lshl_add_u64 v[4:5], v[4:5], 0, s[70:71]
	s_add_i32 m0, s2, 0x1a000
	s_add_i32 s37, s2, 0x8000
	s_add_i32 s38, s2, 0xa000
	global_load_lds_dwordx4 v[4:5], off
	v_lshl_add_u64 v[2:3], v[2:3], 0, s[70:71]
	s_mov_b32 m0, s37
	s_add_u32 s16, s26, 0x8080
	global_load_lds_dwordx4 v[2:3], off
	v_lshl_add_u64 v[2:3], v[8:9], 0, s[70:71]
	s_mov_b32 m0, s38
	s_addc_u32 s17, s27, 0
	global_load_lds_dwordx4 v[2:3], off
	s_add_i32 m0, s2, 0x1c000
	v_lshl_add_u64 v[2:3], s[16:17], 0, v[0:1]
	global_load_lds_dwordx4 v[2:3], off
	v_lshl_add_u64 v[2:3], s[16:17], 0, v[134:135]
	s_add_i32 m0, s2, 0x1e000
	v_lshlrev_b32_e32 v10, 5, v10
	global_load_lds_dwordx4 v[2:3], off
	v_readlane_b32 s16, v251, 35
	v_lshlrev_b32_e32 v2, 2, v10
	v_mov_b32_e32 v3, v1
	v_readlane_b32 s17, v251, 36
	s_cmpk_lt_u32 s12, 0x100
	v_bitop3_b32 v149, s13, v18, v11 bitop3:0xf6
	v_lshl_add_u64 v[136:137], s[16:17], 0, v[2:3]
	v_lshlrev_b32_e32 v2, 15, v15
	v_and_b32_e32 v2, 0xffff0000, v2
	v_lshl_add_u32 v2, v16, 12, v2
	v_and_b32_e32 v3, 1, v15
	v_lshl_or_b32 v2, v3, 6, v2
	v_lshl_add_u32 v138, v17, 1, v2
	v_lshlrev_b32_e32 v2, 15, v12
	s_cselect_b64 s[12:13], -1, 0
	s_lshl_b32 s14, s14, 11
	v_and_b32_e32 v2, 0xffff0000, v2
	s_waitcnt vmcnt(6)
	s_add_i32 s14, s14, 0
	v_lshl_add_u32 v2, v13, 12, v2
	v_and_b32_e32 v3, 1, v12
	s_add_i32 s14, s14, 0x21000
	v_lshl_or_b32 v150, s15, 6, v19
	s_add_i32 s15, 0, 0x20000
	v_lshl_or_b32 v2, v3, 6, v2
	v_lshl_add_u32 v151, v144, 3, s15
	v_lshl_add_u32 v152, v148, 3, s15
	v_lshl_add_u32 v153, v150, 3, s14
	v_mov_b32_e32 v139, v1
	v_lshl_add_u32 v140, v14, 1, v2
	v_mov_b32_e32 v141, v1
	s_lshl_b32 s41, s101, 2
	v_add_u32_e32 v154, 0, v20
	s_barrier
	s_branch .LBB0_165

;     __device__ bool next(int i, Unit& u) const {
;         const int nr = (nwg + G - 1) / G; if (i >= nr) return false;
;         const long L = (long)(rev ? nr - 1 - i : i) * G + c; if (L >= nwg) return false;
;         int wgid = (int)L; { const int q = nwg / NXCD, r = nwg % NXCD, xcd = wgid % NXCD, off = wgid / NXCD; wgid = (xcd < r ? xcd * (q + 1) : r * (q + 1) + (xcd - r) * q) + off; }
; template <class Epi>
; __device__ __forceinline__ void gemm_phase(LAS unsigned char* lds, const Gemm g, const StaticOrder& S, const Epi& E, const int tid) {
;     ...
;         const bool has_next = S.next(ui + 1, nxt);
.LBB0_165:
	s_add_i32 s39, s41, 1
	s_cmp_ge_i32 s39, s100
	s_mov_b64 s[22:23], 0
	s_cbranch_scc1 .LBB0_172
	s_mul_i32 s15, s39, s87
	s_mul_hi_u32 s17, s39, s78
	s_add_i32 s17, s17, s15
	s_mul_i32 s15, s39, s78
	v_readlane_b32 s18, v251, 28
	s_add_u32 s18, s15, s18
	s_addc_u32 s19, s17, s33
	v_mov_b64_e32 v[2:3], 0x7ff
	v_cmp_gt_i64_e32 vcc, s[18:19], v[2:3]
	s_cbranch_vccnz .LBB0_172
	s_ashr_i32 s14, s18, 31
	s_lshr_b32 s14, s14, 29
	s_add_i32 s16, s18, s14
	s_and_b32 s14, s16, -8
	s_sub_i32 s17, s18, s14
	s_cmp_gt_i32 s17, -1
	s_mov_b64 s[14:15], -1
	s_cbranch_scc0 .LBB0_169
	s_lshl_b32 s18, s17, 8
	s_mov_b64 s[14:15], 0
